# retention and SSD inner MFMA loops: LDS fragment reads issued ahead into free registers with counted lgkmcnt waits
# baseline (speedup 1.0000x reference)
; DI bf16x8 cat4(s16x4 lo, s16x4 hi) { return __builtin_shufflevector(lo, hi, 0, 1, 2, 3, 4, 5, 6, 7); }
; DI f32x16 zero16() { f32x16 v; _Pragma("unroll") for (int i = 0; i < 16; ++i) v[i] = 0.f; return v; }
; DI int crow(int i, int h) { return (i & 3) + 8 * (i >> 2) + 4 * h; }
; #define MFMA32(a, b, c) __builtin_amdgcn_mfma_f32_32x32x16_bf16((a), (b), (c), 0, 0, 0)
; DI void ret_prompt_item(char* shm, const Params& P, int l, int hf, int b, int hd) {
;     ...
;     _Pragma("unroll 1") for (int mk = 0; mk <= lt; ++mk) {
;       f32x16 Aa = zero16();
;       _Pragma("unroll") for (int s = 0; s < 4; ++s) Aa = MFMA32(ld8(KK + (mk * 32 + r) * 72 + 16 * s + 8 * hh), qf[s], Aa);
;       if (mk == lt) _Pragma("unroll") for (int i = 0; i < 16; ++i) if (crow(i, hh) > r) Aa[i] = 0.f;
;       const bf16x8 p0 = packP<0>(Aa), p1 = packP<1>(Aa);
;       { const u16* vp = Vt + ((2 * eh) * 32 + r) * 136 + mk * 32 + 4 * hh;
;         O0 = MFMA32(cat4(*(const s16x4*)vp, *(const s16x4*)(vp + 8)), p0, O0);
;         O0 = MFMA32(cat4(*(const s16x4*)(vp + 16), *(const s16x4*)(vp + 24)), p1, O0); }
;       { const u16* vp = Vt + ((2 * eh + 1) * 32 + r) * 136 + mk * 32 + 4 * hh;
;         O1 = MFMA32(cat4(*(const s16x4*)vp, *(const s16x4*)(vp + 8)), p0, O1);
;         O1 = MFMA32(cat4(*(const s16x4*)(vp + 16), *(const s16x4*)(vp + 24)), p1, O1); }
;     }
.LBB0_235:
	s_or_b64 exec, exec, s[44:45]
	s_nop 8
	v_cvt_pk_bf16_f32 v48, v48, v49
	v_cvt_pk_bf16_f32 v49, v50, v51
	v_cvt_pk_bf16_f32 v50, v52, v53
	v_cvt_pk_bf16_f32 v51, v54, v55
	v_cvt_pk_bf16_f32 v52, v56, v57
	v_cvt_pk_bf16_f32 v53, v58, v59
	v_cvt_pk_bf16_f32 v54, v60, v61
	v_cvt_pk_bf16_f32 v55, v62, v63
	s_waitcnt lgkmcnt(0)
	v_mfma_f32_32x32x16_bf16 v[32:47], v[174:177], v[48:51], v[32:47]
	v_add_u32_e32 v161, 1, v161
	v_cmp_eq_u32_e32 vcc, 1, v161
	v_add_u32_e32 v159, 0x1200, v159
	s_or_b64 s[42:43], vcc, s[42:43]
	v_mfma_f32_32x32x16_bf16 v[32:47], v[178:181], v[52:55], v[32:47]
	v_add_u32_e32 v160, 64, v160
	v_mfma_f32_32x32x16_bf16 v[16:31], v[182:185], v[48:51], v[16:31]
	v_mfma_f32_32x32x16_bf16 v[16:31], v[186:189], v[52:55], v[16:31]
	s_andn2_b64 exec, exec, s[42:43]
	s_cbranch_execz .LBB0_231
.LBB0_236:
	ds_read_b128 v[48:51], v159
	ds_read_b128 v[162:165], v159 offset:32
	ds_read_b128 v[166:169], v159 offset:64
	ds_read_b128 v[170:173], v159 offset:96
	v_add_u32_e32 v190, 0x2000, v160
	ds_read2_b64 v[174:177], v160 offset1:2
	ds_read2_b64 v[178:181], v160 offset0:4 offset1:6
	ds_read2_b64 v[182:185], v190 offset0:64 offset1:66
	ds_read2_b64 v[186:189], v190 offset0:68 offset1:70
	v_cmp_eq_u32_e32 vcc, 0, v161
	s_waitcnt lgkmcnt(7)
	v_mfma_f32_32x32x16_bf16 v[48:63], v[48:51], v[98:101], 0
	s_waitcnt lgkmcnt(6)
	v_mfma_f32_32x32x16_bf16 v[48:63], v[162:165], v[102:105], v[48:63]
	s_waitcnt lgkmcnt(5)
	v_mfma_f32_32x32x16_bf16 v[48:63], v[166:169], v[106:109], v[48:63]
	s_waitcnt lgkmcnt(4)
	v_mfma_f32_32x32x16_bf16 v[48:63], v[170:173], v[110:113], v[48:63]
	s_and_saveexec_b64 s[44:45], vcc
	s_cbranch_execz .LBB0_235
	s_nop 9
	v_cndmask_b32_e64 v162, v48, 0, s[4:5]
	v_cndmask_b32_e64 v49, 0, v49, s[6:7]
	v_cndmask_b32_e64 v48, v162, v48, s[6:7]
	v_cndmask_b32_e64 v50, v50, 0, s[8:9]
	v_cndmask_b32_e64 v51, v51, 0, s[10:11]
	v_cndmask_b32_e64 v52, v52, 0, s[12:13]
	v_cndmask_b32_e64 v53, v53, 0, s[14:15]
	v_cndmask_b32_e64 v54, v54, 0, s[16:17]
	v_cndmask_b32_e64 v55, v55, 0, s[18:19]
	v_cndmask_b32_e64 v56, v56, 0, s[20:21]
	v_cndmask_b32_e64 v57, v57, 0, s[22:23]
	v_cndmask_b32_e64 v58, v58, 0, s[24:25]
	v_cndmask_b32_e64 v59, v59, 0, s[26:27]
	v_cndmask_b32_e64 v60, v60, 0, s[28:29]
	v_cndmask_b32_e64 v61, v61, 0, s[30:31]
	v_cndmask_b32_e64 v62, v62, 0, s[34:35]
	v_cndmask_b32_e64 v63, v63, 0, s[36:37]
	s_branch .LBB0_235

; DI bf16x8 cat4(s16x4 lo, s16x4 hi) { return __builtin_shufflevector(lo, hi, 0, 1, 2, 3, 4, 5, 6, 7); }
; DI f32x16 zero16() { f32x16 v; _Pragma("unroll") for (int i = 0; i < 16; ++i) v[i] = 0.f; return v; }
; DI int crow(int i, int h) { return (i & 3) + 8 * (i >> 2) + 4 * h; }
; #define MFMA32(a, b, c) __builtin_amdgcn_mfma_f32_32x32x16_bf16((a), (b), (c), 0, 0, 0)
; DI void ssd_prompt_item(char* shm, const Params& P, int l, int hf, int b, int hc) {
;     ...
;     _Pragma("unroll 1") for (int jt = 0; jt <= it; ++jt) {
;       f32x16 Gm = zero16();
;       _Pragma("unroll") for (int s = 0; s < 8; ++s) Gm = MFMA32(ld8(Bm + (jt * 32 + r) * 136 + 16 * s + 8 * hh), ld8(cfp + 16 * s), Gm);
;       _Pragma("unroll") for (int i = 0; i < 16; ++i) {
;         const int jl = crow(i, hh), j = jt * 32 + jl;
;         const float v = Gm[i] * __expf(ai - acum[j]) * dtv[j];
;         Gm[i] = (jt == it && jl > r) ? 0.f : v;
;       }
;       const bf16x8 p0 = packP<0>(Gm), p1 = packP<1>(Gm);
;       const u16* xp = Xs + (pt * 32 + r) * 136 + jt * 32 + 4 * hh;
;       Y = MFMA32(cat4(*(const s16x4*)xp, *(const s16x4*)(xp + 8)), p0, Y);
;       Y = MFMA32(cat4(*(const s16x4*)(xp + 16), *(const s16x4*)(xp + 24)), p1, Y);
;     }
.LBB0_259:
	v_add_u32_e32 v216, 16, v209
	ds_read_b128 v[32:35], v216
	ds_read_b128 v[212:215], v216 offset:32
	ds_read_b128 v[228:231], v216 offset:64
	ds_read_b128 v[238:241], v216 offset:96
	v_add_u32_e32 v220, 16, v208
	v_cmp_eq_u32_e64 s[0:1], 0, v210
	s_and_b64 s[60:61], s[20:21], s[0:1]
	s_waitcnt lgkmcnt(3)
	v_mfma_f32_32x32x16_bf16 v[32:47], v[32:35], v[90:93], 0
	v_add_u32_e32 v210, 1, v210
	v_add_u32_e32 v209, 0x2200, v209
	v_add_u32_e32 v208, 0x80, v208
	s_waitcnt lgkmcnt(2)
	v_mfma_f32_32x32x16_bf16 v[32:47], v[212:215], v[94:97], v[32:47]
	ds_read_b128 v[212:215], v216 offset:128
	s_waitcnt lgkmcnt(2)
	v_mfma_f32_32x32x16_bf16 v[32:47], v[228:231], v[98:101], v[32:47]
	ds_read_b128 v[228:231], v216 offset:160
	s_waitcnt lgkmcnt(2)
	v_mfma_f32_32x32x16_bf16 v[32:47], v[238:241], v[102:105], v[32:47]
	ds_read_b128 v[238:241], v216 offset:192
	s_waitcnt lgkmcnt(2)
	v_mfma_f32_32x32x16_bf16 v[32:47], v[212:215], v[106:109], v[32:47]
	ds_read_b128 v[212:215], v216 offset:224
	s_waitcnt lgkmcnt(2)
	v_mfma_f32_32x32x16_bf16 v[32:47], v[228:231], v[110:113], v[32:47]
	s_waitcnt lgkmcnt(1)
	v_mfma_f32_32x32x16_bf16 v[32:47], v[238:241], v[114:117], v[32:47]
	s_waitcnt lgkmcnt(0)
	v_mfma_f32_32x32x16_bf16 v[32:47], v[212:215], v[118:121], v[32:47]
	v_add_u32_e32 v212, 0x1dc00, v220
	ds_read_b128 v[212:215], v212
	s_waitcnt lgkmcnt(0)
	v_sub_f32_e32 v212, v207, v212
	v_mul_f32_e32 v212, 0x3fb8aa3b, v212
	v_exp_f32_e32 v212, v212
	s_nop 5
	v_mul_f32_e32 v32, v32, v212
	v_add_u32_e32 v212, 0x1de00, v220
	ds_read_b128 v[216:219], v212
	s_waitcnt lgkmcnt(0)
	v_mul_f32_e32 v32, v216, v32
	v_cndmask_b32_e64 v216, v32, 0, s[60:61]
	v_sub_f32_e32 v32, v207, v213
	v_mul_f32_e32 v32, 0x3fb8aa3b, v32
	v_exp_f32_e32 v32, v32
	s_and_b64 s[60:61], s[22:23], s[0:1]
	v_mul_f32_e32 v32, v33, v32
	v_mul_f32_e32 v32, v217, v32
	v_cndmask_b32_e64 v217, v32, 0, s[60:61]
	v_sub_f32_e32 v32, v207, v214
	v_mul_f32_e32 v32, 0x3fb8aa3b, v32
	v_exp_f32_e32 v32, v32
	s_and_b64 s[60:61], s[24:25], s[0:1]
	v_mul_f32_e32 v32, v34, v32
	v_mul_f32_e32 v32, v218, v32
	v_cndmask_b32_e64 v218, v32, 0, s[60:61]
	v_sub_f32_e32 v32, v207, v215
	v_mul_f32_e32 v32, 0x3fb8aa3b, v32
	v_exp_f32_e32 v32, v32
	s_and_b64 s[60:61], s[26:27], s[0:1]
	v_mul_f32_e32 v32, v35, v32
	v_mul_f32_e32 v32, v219, v32
	v_cndmask_b32_e64 v219, v32, 0, s[60:61]
	v_add_u32_e32 v32, 0x1dc20, v220
	ds_read_b128 v[32:35], v32
	s_and_b64 s[60:61], s[28:29], s[0:1]
	s_waitcnt lgkmcnt(0)
	v_sub_f32_e32 v32, v207, v32
	v_mul_f32_e32 v32, 0x3fb8aa3b, v32
	v_exp_f32_e32 v32, v32
	s_nop 0
	v_mul_f32_e32 v32, v36, v32
	v_add_u32_e32 v36, 0x1de20, v220
	ds_read_b128 v[212:215], v36
	v_add_u32_e32 v36, 0x1de40, v220
	s_waitcnt lgkmcnt(0)
	v_mul_f32_e32 v32, v212, v32
	v_cndmask_b32_e64 v212, v32, 0, s[60:61]
	v_sub_f32_e32 v32, v207, v33
	v_mul_f32_e32 v32, 0x3fb8aa3b, v32
	v_exp_f32_e32 v32, v32
	s_and_b64 s[60:61], s[30:31], s[0:1]
	v_mul_f32_e32 v32, v37, v32
	v_mul_f32_e32 v32, v213, v32
	v_cndmask_b32_e64 v213, v32, 0, s[60:61]
	v_sub_f32_e32 v32, v207, v34
	v_mul_f32_e32 v32, 0x3fb8aa3b, v32
	v_exp_f32_e32 v32, v32
	s_and_b64 s[60:61], s[34:35], s[0:1]
	v_mul_f32_e32 v32, v38, v32
	v_mul_f32_e32 v32, v214, v32
	v_cndmask_b32_e64 v214, v32, 0, s[60:61]
	v_sub_f32_e32 v32, v207, v35
	v_mul_f32_e32 v32, 0x3fb8aa3b, v32
	v_exp_f32_e32 v32, v32
	s_and_b64 s[60:61], s[36:37], s[0:1]
	v_mul_f32_e32 v32, v39, v32
	v_mul_f32_e32 v32, v215, v32
	v_cndmask_b32_e64 v215, v32, 0, s[60:61]
	v_add_u32_e32 v32, 0x1dc40, v220
	ds_read_b128 v[32:35], v32
	ds_read_b128 v[36:39], v36
	s_and_b64 s[60:61], s[38:39], s[0:1]
	s_waitcnt lgkmcnt(1)
	v_sub_f32_e32 v32, v207, v32
	v_mul_f32_e32 v32, 0x3fb8aa3b, v32
	v_exp_f32_e32 v32, v32
	s_nop 0
	v_mul_f32_e32 v32, v40, v32
	s_waitcnt lgkmcnt(0)
	v_mul_f32_e32 v32, v36, v32
	v_cndmask_b32_e64 v40, v32, 0, s[60:61]
	v_sub_f32_e32 v32, v207, v33
	v_mul_f32_e32 v32, 0x3fb8aa3b, v32
	v_exp_f32_e32 v32, v32
	s_and_b64 s[60:61], s[40:41], s[0:1]
	v_add_u32_e32 v36, 0x1de60, v220
	v_mul_f32_e32 v32, v41, v32
	v_mul_f32_e32 v32, v37, v32
	v_cndmask_b32_e64 v41, v32, 0, s[60:61]
	v_sub_f32_e32 v32, v207, v34
	v_mul_f32_e32 v32, 0x3fb8aa3b, v32
	v_exp_f32_e32 v32, v32
	s_and_b64 s[60:61], s[42:43], s[0:1]
	v_mul_f32_e32 v32, v42, v32
	v_mul_f32_e32 v32, v38, v32
	v_cndmask_b32_e64 v42, v32, 0, s[60:61]
	v_sub_f32_e32 v32, v207, v35
	v_mul_f32_e32 v32, 0x3fb8aa3b, v32
	v_exp_f32_e32 v32, v32
	s_and_b64 s[60:61], s[44:45], s[0:1]
	v_mul_f32_e32 v32, v43, v32
	v_mul_f32_e32 v32, v39, v32
	v_cndmask_b32_e64 v43, v32, 0, s[60:61]
	v_add_u32_e32 v32, 0x1dc60, v220
	ds_read_b128 v[32:35], v32
	ds_read_b128 v[36:39], v36
	s_and_b64 s[60:61], s[46:47], s[0:1]
	s_waitcnt lgkmcnt(1)
	v_sub_f32_e32 v32, v207, v32
	v_mul_f32_e32 v32, 0x3fb8aa3b, v32
	v_exp_f32_e32 v32, v32
	s_nop 0
	v_mul_f32_e32 v32, v44, v32
	s_waitcnt lgkmcnt(0)
	v_mul_f32_e32 v32, v36, v32
	v_cndmask_b32_e64 v44, v32, 0, s[60:61]
	v_sub_f32_e32 v32, v207, v33
	v_mul_f32_e32 v32, 0x3fb8aa3b, v32
	v_exp_f32_e32 v32, v32
	s_and_b64 s[60:61], s[48:49], s[0:1]
	v_cvt_pk_bf16_f32 v33, v42, v43
	v_cvt_pk_bf16_f32 v36, v216, v217
	v_mul_f32_e32 v32, v45, v32
	v_mul_f32_e32 v32, v37, v32
	v_cndmask_b32_e64 v45, v32, 0, s[60:61]
	v_sub_f32_e32 v32, v207, v34
	v_mul_f32_e32 v32, 0x3fb8aa3b, v32
	v_exp_f32_e32 v32, v32
	s_and_b64 s[60:61], s[50:51], s[0:1]
	s_and_b64 s[0:1], s[52:53], s[0:1]
	v_cvt_pk_bf16_f32 v34, v44, v45
	v_mul_f32_e32 v32, v46, v32
	v_mul_f32_e32 v32, v38, v32
	v_cndmask_b32_e64 v46, v32, 0, s[60:61]
	v_sub_f32_e32 v32, v207, v35
	v_mul_f32_e32 v32, 0x3fb8aa3b, v32
	v_exp_f32_e32 v32, v32
	v_add_u32_e32 v44, 16, v211
	v_add_u32_e32 v42, 0x11010, v44
	ds_read_b64 v[42:43], v42
	v_mul_f32_e32 v32, v47, v32
	v_mul_f32_e32 v32, v39, v32
	v_cndmask_b32_e64 v35, v32, 0, s[0:1]
	v_cvt_pk_bf16_f32 v32, v40, v41
	v_add_u32_e32 v40, 0x11000, v44
	ds_read_b64 v[40:41], v40
	v_cvt_pk_bf16_f32 v37, v218, v219
	v_cvt_pk_bf16_f32 v38, v212, v213
	v_cvt_pk_bf16_f32 v39, v214, v215
	v_cvt_pk_bf16_f32 v35, v46, v35
	v_cmp_eq_u32_e64 s[0:1], 1, v210
	s_waitcnt lgkmcnt(0)
	v_mfma_f32_32x32x16_bf16 v[16:31], v[40:43], v[36:39], v[16:31]
	v_add_u32_e32 v36, 0x11020, v44
	v_add_u32_e32 v38, 0x11030, v44
	ds_read_b64 v[36:37], v36
	ds_read_b64 v[38:39], v38
	v_add_u32_e32 v211, 64, v211
	s_or_b64 s[88:89], s[0:1], s[88:89]
	s_waitcnt lgkmcnt(0)
	v_mfma_f32_32x32x16_bf16 v[16:31], v[36:39], v[32:35], v[16:31]
	s_andn2_b64 exec, exec, s[88:89]
	s_cbranch_execnz .LBB0_259
; DI float bf2f(u16 h) { return __uint_as_float(((unsigned)h) << 16); }
; DI int crow(int i, int h) { return (i & 3) + 8 * (i >> 2) + 4 * h; }
; #define MFMA32(a, b, c) __builtin_amdgcn_mfma_f32_32x32x16_bf16((a), (b), (c), 0, 0, 0)
; DI void st4bf(u16* p, float a, float b, float c, float d) { u32x2 v; v[0] = pack2(a, b); v[1] = pack2(c, d); *reinterpret_cast<u32x2*>(p) = v; }
; DI void ssd_prompt_item(char* shm, const Params& P, int l, int hf, int b, int hc) {
;     ...
;     _Pragma("unroll") for (int i = 0; i < 16; ++i) Y[i] += dsk * bf2f(Xs[(pt * 32 + crow(i, hh)) * 136 + it * 32 + r]);
;     { u16* yrow = YC + (size_t)(lrowb + tok0 + it * 32 + r) * D + hc * 64 + pt * 32;
;       _Pragma("unroll") for (int gq = 0; gq < 4; ++gq) st4bf(yrow + 8 * gq + 4 * hh, Y[4 * gq], Y[4 * gq + 1], Y[4 * gq + 2], Y[4 * gq + 3]); }
;     { const float dl = __expf(alast); _Pragma("unroll") for (int i = 0; i < 16; ++i) Hacc[i] *= dl; }
;     _Pragma("unroll") for (int s = 0; s < 8; ++s) {
;       const bf16x8 xf = ld8(XwT + (pt * 32 + r) * 136 + 16 * s + 8 * hh);
;       const u16* bp = Bm + (16 * s + 8 * hh) * 136 + it * 32 + r;
;       u32x4 pb;
;       _Pragma("unroll") for (int q = 0; q < 4; ++q) pb[q] = (unsigned)bp[(2 * q) * 136] | ((unsigned)bp[(2 * q + 1) * 136] << 16);
;       Hacc = MFMA32(xf, __builtin_bit_cast(bf16x8, pb), Hacc);
;     }
	s_or_b64 exec, exec, s[88:89]
	ds_read_u16 v32, v204
	ds_read_u16 v33, v204 offset:272
	s_cmp_eq_u32 s81, 16
	s_waitcnt lgkmcnt(1)
	v_lshlrev_b32_e32 v32, 16, v32
	s_waitcnt lgkmcnt(0)
	v_lshlrev_b32_e32 v33, 16, v33
	s_nop 1
	v_pk_fma_f32 v[16:17], v[124:125], v[32:33], v[16:17]
	ds_read_u16 v32, v204 offset:544
	ds_read_u16 v33, v204 offset:816
	v_cvt_pk_bf16_f32 v16, v16, v17
	s_waitcnt lgkmcnt(1)
	v_lshlrev_b32_e32 v32, 16, v32
	s_waitcnt lgkmcnt(0)
	v_lshlrev_b32_e32 v33, 16, v33
	v_pk_fma_f32 v[18:19], v[124:125], v[32:33], v[18:19]
	ds_read_u16 v32, v204 offset:2176
	ds_read_u16 v33, v204 offset:2448
	v_cvt_pk_bf16_f32 v17, v18, v19
	s_waitcnt lgkmcnt(1)
	v_lshlrev_b32_e32 v32, 16, v32
	s_waitcnt lgkmcnt(0)
	v_lshlrev_b32_e32 v33, 16, v33
	v_pk_fma_f32 v[20:21], v[124:125], v[32:33], v[20:21]
	ds_read_u16 v32, v204 offset:2720
	ds_read_u16 v33, v204 offset:2992
	s_waitcnt lgkmcnt(1)
	v_lshlrev_b32_e32 v32, 16, v32
	s_waitcnt lgkmcnt(0)
	v_lshlrev_b32_e32 v33, 16, v33
	v_pk_fma_f32 v[22:23], v[124:125], v[32:33], v[22:23]
	ds_read_u16 v32, v204 offset:4352
	ds_read_u16 v33, v204 offset:4624
	s_waitcnt lgkmcnt(1)
	v_lshlrev_b32_e32 v32, 16, v32
	s_waitcnt lgkmcnt(0)
	v_lshlrev_b32_e32 v33, 16, v33
	v_pk_fma_f32 v[24:25], v[124:125], v[32:33], v[24:25]
	ds_read_u16 v32, v204 offset:4896
	ds_read_u16 v33, v204 offset:5168
	s_waitcnt lgkmcnt(1)
	v_lshlrev_b32_e32 v32, 16, v32
	s_waitcnt lgkmcnt(0)
	v_lshlrev_b32_e32 v33, 16, v33
	v_pk_fma_f32 v[26:27], v[124:125], v[32:33], v[26:27]
	ds_read_u16 v32, v204 offset:6528
	ds_read_u16 v33, v204 offset:6800
	s_waitcnt lgkmcnt(1)
	v_lshlrev_b32_e32 v32, 16, v32
	s_waitcnt lgkmcnt(0)
	v_lshlrev_b32_e32 v33, 16, v33
	v_pk_fma_f32 v[28:29], v[124:125], v[32:33], v[28:29]
	ds_read_u16 v32, v204 offset:7072
	ds_read_u16 v33, v204 offset:7344
	s_waitcnt lgkmcnt(1)
	v_lshlrev_b32_e32 v32, 16, v32
	s_waitcnt lgkmcnt(0)
	v_lshlrev_b32_e32 v33, 16, v33
	v_pk_fma_f32 v[30:31], v[124:125], v[32:33], v[30:31]
	v_lshl_add_u32 v32, s96, 7, v163
	v_ashrrev_i32_e32 v33, 31, v32
	v_lshlrev_b64 v[32:33], 11, v[32:33]
	v_lshl_add_u64 v[32:33], v[134:135], 0, v[32:33]
	global_store_dwordx2 v[32:33], v[16:17], off
	v_cvt_pk_bf16_f32 v16, v20, v21
	v_cvt_pk_bf16_f32 v17, v22, v23
	global_store_dwordx2 v[32:33], v[16:17], off offset:16
	v_cvt_pk_bf16_f32 v16, v24, v25
	v_cvt_pk_bf16_f32 v17, v26, v27
	global_store_dwordx2 v[32:33], v[16:17], off offset:32
	v_cvt_pk_bf16_f32 v16, v28, v29
	v_cvt_pk_bf16_f32 v17, v30, v31
	global_store_dwordx2 v[32:33], v[16:17], off offset:48
	v_mul_f32_e32 v16, 0x3fb8aa3b, v206
	v_exp_f32_e32 v16, v16
	s_mov_b32 s96, s81
	v_pk_mul_f32 v[14:15], v[14:15], v[16:17] op_sel_hi:[1,0]
	v_pk_mul_f32 v[12:13], v[12:13], v[16:17] op_sel_hi:[1,0]
	v_pk_mul_f32 v[10:11], v[10:11], v[16:17] op_sel_hi:[1,0]
	v_pk_mul_f32 v[8:9], v[8:9], v[16:17] op_sel_hi:[1,0]
	v_pk_mul_f32 v[6:7], v[6:7], v[16:17] op_sel_hi:[1,0]
	v_pk_mul_f32 v[4:5], v[4:5], v[16:17] op_sel_hi:[1,0]
	v_pk_mul_f32 v[2:3], v[2:3], v[16:17] op_sel_hi:[1,0]
	v_pk_mul_f32 v[0:1], v[0:1], v[16:17] op_sel_hi:[1,0]
	ds_read_u16 v16, v201
	ds_read_u16 v17, v201 offset:272
	s_waitcnt lgkmcnt(0)
	v_lshl_or_b32 v16, v17, 16, v16
	ds_read_u16 v17, v201 offset:544
	ds_read_u16 v18, v201 offset:816
	s_waitcnt lgkmcnt(0)
	v_lshl_or_b32 v17, v18, 16, v17
	ds_read_u16 v18, v201 offset:1088
	ds_read_u16 v19, v201 offset:1360
	s_waitcnt lgkmcnt(0)
	v_lshl_or_b32 v18, v19, 16, v18
	ds_read_u16 v19, v201 offset:1632
	ds_read_u16 v20, v201 offset:1904
	s_waitcnt lgkmcnt(0)
	v_lshl_or_b32 v19, v20, 16, v19
	ds_read_b128 v[20:23], v164
	ds_read_b128 v[24:27], v164 offset:32
	s_waitcnt lgkmcnt(1)
	v_mfma_f32_32x32x16_bf16 v[0:15], v[20:23], v[16:19], v[0:15]
	ds_read_u16 v16, v201 offset:4352
	ds_read_u16 v17, v201 offset:4624
	s_waitcnt lgkmcnt(0)
	v_lshl_or_b32 v16, v17, 16, v16
	ds_read_u16 v17, v201 offset:4896
	ds_read_u16 v18, v201 offset:5168
	s_waitcnt lgkmcnt(0)
	v_lshl_or_b32 v17, v18, 16, v17
	ds_read_u16 v18, v201 offset:5440
	ds_read_u16 v19, v201 offset:5712
	s_waitcnt lgkmcnt(0)
	v_lshl_or_b32 v18, v19, 16, v18
	ds_read_u16 v19, v201 offset:5984
	ds_read_u16 v20, v201 offset:6256
	s_waitcnt lgkmcnt(0)
	v_lshl_or_b32 v19, v20, 16, v19
	s_nop 1
	v_mfma_f32_32x32x16_bf16 v[0:15], v[24:27], v[16:19], v[0:15]
	ds_read_b128 v[16:19], v164 offset:64
	ds_read_u16 v20, v201 offset:8704
	ds_read_u16 v21, v201 offset:8976
	s_waitcnt lgkmcnt(0)
	v_lshl_or_b32 v20, v21, 16, v20
	ds_read_u16 v21, v201 offset:9248
	ds_read_u16 v22, v201 offset:9520
	s_waitcnt lgkmcnt(0)
	v_lshl_or_b32 v21, v22, 16, v21
	ds_read_u16 v22, v201 offset:9792
	ds_read_u16 v23, v201 offset:10064
	s_waitcnt lgkmcnt(0)
	v_lshl_or_b32 v22, v23, 16, v22
	ds_read_u16 v23, v201 offset:10336
	ds_read_u16 v24, v201 offset:10608
	s_waitcnt lgkmcnt(0)
	v_lshl_or_b32 v23, v24, 16, v23
	s_nop 1
	v_mfma_f32_32x32x16_bf16 v[0:15], v[16:19], v[20:23], v[0:15]
	ds_read_b128 v[16:19], v164 offset:96
	ds_read_u16 v20, v201 offset:13056
	ds_read_u16 v21, v201 offset:13328
	s_waitcnt lgkmcnt(0)
	v_lshl_or_b32 v20, v21, 16, v20
	ds_read_u16 v21, v201 offset:13600
	ds_read_u16 v22, v201 offset:13872
	s_waitcnt lgkmcnt(0)
	v_lshl_or_b32 v21, v22, 16, v21
	ds_read_u16 v22, v201 offset:14144
	ds_read_u16 v23, v201 offset:14416
	s_waitcnt lgkmcnt(0)
	v_lshl_or_b32 v22, v23, 16, v22
	ds_read_u16 v23, v201 offset:14688
	ds_read_u16 v24, v201 offset:14960
	s_waitcnt lgkmcnt(0)
	v_lshl_or_b32 v23, v24, 16, v23
	s_nop 1
	v_mfma_f32_32x32x16_bf16 v[0:15], v[16:19], v[20:23], v[0:15]
	ds_read_b128 v[16:19], v164 offset:128
	ds_read_u16 v20, v201 offset:17408
	ds_read_u16 v21, v201 offset:17680
	s_waitcnt lgkmcnt(0)
; DI u16 f2bf(float x) { return (u16)(pack2(x, 0.f) & 0xffffu); }
; DI float bf2f(u16 h) { return __uint_as_float(((unsigned)h) << 16); }
; DI int crow(int i, int h) { return (i & 3) + 8 * (i >> 2) + 4 * h; }
; #define MFMA32(a, b, c) __builtin_amdgcn_mfma_f32_32x32x16_bf16((a), (b), (c), 0, 0, 0)
; DI void ssd_prompt_item(char* shm, const Params& P, int l, int hf, int b, int hc) {
;     ...
;     _Pragma("unroll") for (int s = 0; s < 8; ++s) {
;       const bf16x8 xf = ld8(XwT + (pt * 32 + r) * 136 + 16 * s + 8 * hh);
;       const u16* bp = Bm + (16 * s + 8 * hh) * 136 + it * 32 + r;
;       u32x4 pb;
;       _Pragma("unroll") for (int q = 0; q < 4; ++q) pb[q] = (unsigned)bp[(2 * q) * 136] | ((unsigned)bp[(2 * q + 1) * 136] << 16);
;       Hacc = MFMA32(xf, __builtin_bit_cast(bf16x8, pb), Hacc);
;     }
;     __syncthreads();
;     _Pragma("unroll") for (int i = 0; i < 16; ++i) Hs[(pt * 32 + crow(i, hh)) * 136 + it * 32 + r] = f2bf(Hacc[i]);
;   }
;   { float* ho = P.out + O_SSMP + (size_t)((l * 16 + b) * 16 + hc) * 8192;
;     _Pragma("unroll") for (int i = 0; i < 16; ++i) ho[(pt * 32 + crow(i, hh)) * 128 + it * 32 + r] = Hacc[i]; }
;   { float* co = P.out + O_CONVP + (size_t)(l * 16 + b) * 3 * 1536;
;     for (int e = tid; e < 3 * 64; e += NT) { const int i = e >> 6, ch = hc * 64 + (e & 63); co[i * 1536 + ch] = bf2f(Z[(size_t)(lrowb + 2045 + i) * ZS + C_CX + ch]); }
;     if ((hc & 7) == 0) for (int e = tid; e < 3 * 256; e += NT) { const int i = e >> 8, q = e & 255; const int ch = (q < 128 ? 1024 : 1280 - 128) + g * 128 + q; co[i * 1536 + ch] = bf2f(Z[(size_t)(lrowb + 2045 + i) * ZS + C_CX + ch]); } }
	v_lshl_or_b32 v20, v21, 16, v20
	ds_read_u16 v21, v201 offset:17952
	ds_read_u16 v22, v201 offset:18224
	s_waitcnt lgkmcnt(0)
	v_lshl_or_b32 v21, v22, 16, v21
	ds_read_u16 v22, v201 offset:18496
	ds_read_u16 v23, v201 offset:18768
	s_waitcnt lgkmcnt(0)
	v_lshl_or_b32 v22, v23, 16, v22
	ds_read_u16 v23, v201 offset:19040
	ds_read_u16 v24, v201 offset:19312
	s_waitcnt lgkmcnt(0)
	v_lshl_or_b32 v23, v24, 16, v23
	s_nop 1
	v_mfma_f32_32x32x16_bf16 v[0:15], v[16:19], v[20:23], v[0:15]
	ds_read_b128 v[16:19], v164 offset:160
	ds_read_u16 v20, v201 offset:21760
	ds_read_u16 v21, v201 offset:22032
	s_waitcnt lgkmcnt(0)
	v_lshl_or_b32 v20, v21, 16, v20
	ds_read_u16 v21, v201 offset:22304
	ds_read_u16 v22, v201 offset:22576
	s_waitcnt lgkmcnt(0)
	v_lshl_or_b32 v21, v22, 16, v21
	ds_read_u16 v22, v201 offset:22848
	ds_read_u16 v23, v201 offset:23120
	s_waitcnt lgkmcnt(0)
	v_lshl_or_b32 v22, v23, 16, v22
	ds_read_u16 v23, v201 offset:23392
	ds_read_u16 v24, v201 offset:23664
	s_waitcnt lgkmcnt(0)
	v_lshl_or_b32 v23, v24, 16, v23
	s_nop 1
	v_mfma_f32_32x32x16_bf16 v[0:15], v[16:19], v[20:23], v[0:15]
	ds_read_b128 v[16:19], v164 offset:192
	ds_read_u16 v20, v201 offset:26112
	ds_read_u16 v21, v201 offset:26384
	s_waitcnt lgkmcnt(0)
	v_lshl_or_b32 v20, v21, 16, v20
	ds_read_u16 v21, v201 offset:26656
	ds_read_u16 v22, v201 offset:26928
	s_waitcnt lgkmcnt(0)
	v_lshl_or_b32 v21, v22, 16, v21
	ds_read_u16 v22, v201 offset:27200
	ds_read_u16 v23, v201 offset:27472
	s_waitcnt lgkmcnt(0)
	v_lshl_or_b32 v22, v23, 16, v22
	ds_read_u16 v23, v201 offset:27744
	ds_read_u16 v24, v201 offset:28016
	s_waitcnt lgkmcnt(0)
	v_lshl_or_b32 v23, v24, 16, v23
	s_nop 1
	v_mfma_f32_32x32x16_bf16 v[0:15], v[16:19], v[20:23], v[0:15]
	ds_read_b128 v[16:19], v164 offset:224
	ds_read_u16 v20, v201 offset:30464
	ds_read_u16 v21, v201 offset:30736
	s_waitcnt lgkmcnt(0)
	v_lshl_or_b32 v20, v21, 16, v20
	ds_read_u16 v21, v201 offset:31008
	ds_read_u16 v22, v201 offset:31280
	s_waitcnt lgkmcnt(0)
	v_lshl_or_b32 v21, v22, 16, v21
	ds_read_u16 v22, v201 offset:31552
	ds_read_u16 v23, v201 offset:31824
	s_waitcnt lgkmcnt(0)
	v_lshl_or_b32 v22, v23, 16, v22
	ds_read_u16 v23, v201 offset:32096
	ds_read_u16 v24, v201 offset:32368
	s_waitcnt lgkmcnt(0)
	s_barrier
	v_lshl_or_b32 v23, v24, 16, v23
	s_nop 1
	v_mfma_f32_32x32x16_bf16 v[0:15], v[16:19], v[20:23], v[0:15]
	s_nop 11
	v_cvt_pk_bf16_f32 v16, v0, s0
	ds_write_b16 v205, v16
	v_cvt_pk_bf16_f32 v16, v1, s0
	ds_write_b16 v205, v16 offset:272
	v_cvt_pk_bf16_f32 v16, v2, s0
	ds_write_b16 v205, v16 offset:544
	v_cvt_pk_bf16_f32 v16, v3, s0
	ds_write_b16 v205, v16 offset:816
	v_cvt_pk_bf16_f32 v16, v4, s0
	ds_write_b16 v205, v16 offset:2176
	v_cvt_pk_bf16_f32 v16, v5, s0
	ds_write_b16 v205, v16 offset:2448
	v_cvt_pk_bf16_f32 v16, v6, s0
	ds_write_b16 v205, v16 offset:2720
	v_cvt_pk_bf16_f32 v16, v7, s0
	ds_write_b16 v205, v16 offset:2992
	v_cvt_pk_bf16_f32 v16, v8, s0
	ds_write_b16 v205, v16 offset:4352
	v_cvt_pk_bf16_f32 v16, v9, s0
	ds_write_b16 v205, v16 offset:4624
	v_cvt_pk_bf16_f32 v16, v10, s0
	ds_write_b16 v205, v16 offset:4896
	v_cvt_pk_bf16_f32 v16, v11, s0
	ds_write_b16 v205, v16 offset:5168
	v_cvt_pk_bf16_f32 v16, v12, s0
	ds_write_b16 v205, v16 offset:6528
	v_cvt_pk_bf16_f32 v16, v13, s0
	ds_write_b16 v205, v16 offset:6800
	v_cvt_pk_bf16_f32 v16, v14, s0
	ds_write_b16 v205, v16 offset:7072
	v_cvt_pk_bf16_f32 v16, v15, s0
	ds_write_b16 v205, v16 offset:7344
	s_cbranch_scc0 .LBB0_249
	s_add_u32 s0, s56, 0xad44000
	s_addc_u32 s1, s57, 0
	s_add_i32 s6, s80, s83
	s_lshl_b32 s4, s6, 4
	s_or_b32 s4, s4, s84
	s_ashr_i32 s5, s4, 31
	v_lshlrev_b32_e32 v16, 12, v152
	s_lshl_b64 s[4:5], s[4:5], 15
	v_readlane_b32 s3, v253, 21
	v_lshl_or_b32 v16, v154, 9, v16
	s_add_u32 s4, s3, s4
	v_readlane_b32 s3, v253, 22
	v_or3_b32 v16, v16, v155, v153
	s_addc_u32 s5, s3, s5
	v_ashrrev_i32_e32 v17, 31, v16
	v_lshl_add_u64 v[16:17], v[16:17], 2, s[4:5]
	s_movk_i32 s60, 0x1000
	global_store_dword v[16:17], v0, off
	global_store_dword v[16:17], v1, off offset:512
	global_store_dword v[16:17], v2, off offset:1024
	global_store_dword v[16:17], v3, off offset:1536
	v_add_co_u32_e32 v0, vcc, s60, v16
	s_movk_i32 s61, 0x3000
	s_nop 0
	v_addc_co_u32_e32 v1, vcc, 0, v17, vcc
	v_add_co_u32_e32 v2, vcc, s92, v16
	s_mul_hi_i32 s5, s6, 0x4800
	s_nop 0
	v_addc_co_u32_e32 v3, vcc, 0, v17, vcc
	s_mulk_i32 s6, 0x4800
	v_readlane_b32 s3, v253, 23
	global_store_dword v[2:3], v4, off offset:-4096
	global_store_dword v[0:1], v5, off offset:512
	global_store_dword v[0:1], v6, off offset:1024
	global_store_dword v[0:1], v7, off offset:1536
	global_store_dword v[2:3], v8, off
	global_store_dword v[2:3], v9, off offset:512
	global_store_dword v[2:3], v10, off offset:1024
	global_store_dword v[2:3], v11, off offset:1536
	v_add_co_u32_e32 v0, vcc, s61, v16
	s_add_u32 s4, s3, s6
	v_readlane_b32 s3, v253, 24
	v_addc_co_u32_e32 v1, vcc, 0, v17, vcc
	s_addc_u32 s5, s3, s5
	s_movk_i32 s3, 0xc0
	v_cmp_gt_i32_e32 vcc, s3, v122
	global_store_dword v[0:1], v12, off
	global_store_dword v[0:1], v13, off offset:512
	global_store_dword v[0:1], v14, off offset:1024
	global_store_dword v[0:1], v15, off offset:1536
	s_and_saveexec_b64 s[6:7], vcc
	v_readlane_b32 s52, v254, 49
	s_mov_b32 s56, 0x800000
	s_movk_i32 s57, 0x4000
	s_movk_i32 s80, 0x90
	v_readlane_b32 s53, v254, 50
	s_cbranch_execz .LBB0_269
	v_max_i32_e32 v1, 0xfffffec0, v122
	v_sub_u32_e32 v1, v1, v122
	v_add_u32_e32 v1, 0x1ff, v1
	s_movk_i32 s3, 0x1ff
	s_or_b32 s12, s78, 0x7fd
	v_or_b32_e32 v0, s82, v133
	v_cmp_lt_u32_e32 vcc, s3, v1
	s_mov_b64 s[10:11], -1
	v_mov_b32_e32 v2, v122
	s_and_saveexec_b64 s[8:9], vcc
	s_cbranch_execz .LBB0_266
	v_lshrrev_b32_e32 v1, 9, v1
	v_add_u32_e32 v1, 1, v1
	v_and_b32_e32 v4, 0xfffffe, v1
	s_mov_b32 s13, s12
	s_mov_b64 s[10:11], 0
	v_mov_b32_e32 v5, v4
	v_mov_b64_e32 v[2:3], v[122:123]
